# scan workgroups no longer join the phase-4 GEMM work queue after their scan (they took a last unit and became the phase's critical path)
# speedup vs baseline: 1.0142x; 1.0142x over previous
;     __device__ __forceinline__ bool leader() const { int l; asm volatile("v_mbcnt_lo_u32_b32 %0, -1, 0\n\tv_mbcnt_hi_u32_b32 %0, -1, %0" : "=v"(l)); return wave0 == 0 && l == 0; }
; #define LAS __attribute__((address_space(3)))
;     __device__ __forceinline__ bool next(int i, Unit& u) const {
;         if (i == 0) { if (leader()) { ring[0] = __hip_atomic_fetch_add(ctr, 1u, __ATOMIC_RELAXED, __HIP_MEMORY_SCOPE_AGENT); ring[1] = __hip_atomic_fetch_add(ctr, 1u, __ATOMIC_RELAXED, __HIP_MEMORY_SCOPE_AGENT); }
;                       __syncthreads(); }
; __global__ void __launch_bounds__(NWAVES * 64, 2) hybrid_fwd(Args A) {
;     ...
;         int sidx = -1;
;         if (G >= 256) { if ((vcu & 31) < 12 && vcu < 256) sidx = (vcu >> 5) * 12 + (vcu & 31); }
;         if (!(A.flags & 1)) {
;             if (sidx >= 0) scan_unit(A, lds, sidx, tid);
;             else if (G < 256) { for (int s = bx; s < 96; s += G) scan_unit(A, lds, s, tid); }
;         }
;         if (!(A.flags & 2)) {
;             __syncthreads();
;             pg8::Gemm g{H, WinT + (size_t)5888 * DMODEL, M, 8960, DMODEL}; pg8::QueueSched S{ctl + 128, (volatile LAS unsigned*)(MISC + 16), 32 * 35, 35, wave0};
;             pg8::EpiIn E{ws, attn_body::C2, 23};
;             pg8::gemm_phase<pg8::EpiIn, pg8::QueueSched, PG8_ALIGN, PG8_SP2>(lds, g, S, E, TIDNOW);
.LBB0_511:
	s_cmp_lt_u32 s97, 96
	s_cbranch_scc1 .LBB0_579
	s_bitcmp1_b32 s58, 1
	s_cbranch_scc1 .LBB0_579
	v_readlane_b32 s1, v254, 8
	s_barrier
	v_mbcnt_lo_u32_b32 v0, -1, 0
	v_mbcnt_hi_u32_b32 v0, -1, v0
	s_cmp_lt_u32 s1, 64
	v_add_u32_e32 v8, s31, v0
	v_mbcnt_lo_u32_b32 v0, -1, 0
	v_mbcnt_hi_u32_b32 v0, -1, v0
	s_cselect_b64 s[4:5], -1, 0
	v_cmp_eq_u32_e32 vcc, 0, v0
	v_readfirstlane_b32 s0, v8
	s_and_b64 s[6:7], s[4:5], vcc
	s_and_saveexec_b64 s[2:3], s[6:7]
	s_cbranch_execz .LBB0_514
	v_mov_b32_e32 v2, 1
	s_waitcnt vmcnt(2)
	v_mov_b64_e32 v[0:1], s[12:13]
	flat_atomic_add v3, v[0:1], v2 offset:512 sc0
	s_add_i32 s1, 0, 0x27f40
	v_mov_b32_e32 v4, s1
	s_add_i32 s1, 0, 0x27f44
	s_waitcnt vmcnt(0) lgkmcnt(0)
	ds_write_b32 v4, v3
	flat_atomic_add v0, v[0:1], v2 offset:512 sc0
	v_mov_b32_e32 v1, s1
	s_waitcnt vmcnt(0) lgkmcnt(0)
	ds_write_b32 v1, v0
